# E3: main-loop LDS-DMA uses SGPR-base (saddr) form, no v_lshl_add_u64
# speedup vs baseline: 1.0019x; 1.0019x over previous
.LBB0_294:
	s_add_i32 s22, s10, 2
	s_add_u32 s23, s2, 0x80
	s_addc_u32 s11, s3, 0
	s_add_i32 s41, 0, 0x10000
	s_cmp_eq_u32 s75, s10
	s_cselect_b32 s11, s83, s11
	s_cselect_b32 s10, s82, s23
	v_add_u32_e32 v0, s41, v153
	s_cselect_b32 s45, s95, s21
	s_cselect_b32 s44, s94, s20
	s_add_i32 s23, 0, 0x14000
	ds_read_b128 v[130:133], v0
	ds_read_b128 v[134:137], v0 offset:1024
	ds_read_b128 v[160:163], v0 offset:2048
	ds_read_b128 v[164:167], v0 offset:3072
	v_add_u32_e32 v0, s23, v153
	ds_read_b128 v[168:171], v0
	ds_read_b128 v[172:175], v0 offset:1024
	ds_read_b128 v[202:205], v0 offset:2048
	ds_read_b128 v[206:209], v0 offset:3072
	s_add_i32 m0, s29, 0xc000
	ds_read_b128 v[210:213], v201
	ds_read_b128 v[214:217], v201 offset:1024
	ds_read_b128 v[218:221], v201 offset:2048
	ds_read_b128 v[222:225], v201 offset:3072
	ds_read_b128 v[226:229], v201 offset:4096
	ds_read_b128 v[230:233], v201 offset:5120
	ds_read_b128 v[234:237], v201 offset:6144
	ds_read_b128 v[238:241], v201 offset:7168
	global_load_lds_dwordx4 v156, s[2:3]
	s_add_i32 m0, s29, 0xe000
	s_nop 0
	global_load_lds_dwordx4 v158, s[2:3]
	s_waitcnt vmcnt(8)
	s_waitcnt lgkmcnt(0)
	s_barrier
	s_setprio 1
	s_waitcnt lgkmcnt(0)
	v_mfma_f32_16x16x32_bf16 v[126:129], v[130:133], v[210:213], v[126:129]
	v_mfma_f32_16x16x32_bf16 v[122:125], v[160:163], v[210:213], v[122:125]
	v_mfma_f32_16x16x32_bf16 v[110:113], v[130:133], v[218:221], v[110:113]
	v_mfma_f32_16x16x32_bf16 v[106:109], v[160:163], v[218:221], v[106:109]
	v_mfma_f32_16x16x32_bf16 v[94:97], v[130:133], v[226:229], v[94:97]
	v_mfma_f32_16x16x32_bf16 v[90:93], v[160:163], v[226:229], v[90:93]
	v_mfma_f32_16x16x32_bf16 v[78:81], v[130:133], v[234:237], v[78:81]
	v_mfma_f32_16x16x32_bf16 v[74:77], v[160:163], v[234:237], v[74:77]
	v_mfma_f32_16x16x32_bf16 v[126:129], v[134:137], v[214:217], v[126:129]
	v_mfma_f32_16x16x32_bf16 v[122:125], v[164:167], v[214:217], v[122:125]
	v_mfma_f32_16x16x32_bf16 v[110:113], v[134:137], v[222:225], v[110:113]
	v_mfma_f32_16x16x32_bf16 v[106:109], v[164:167], v[222:225], v[106:109]
	v_mfma_f32_16x16x32_bf16 v[94:97], v[134:137], v[230:233], v[94:97]
	v_mfma_f32_16x16x32_bf16 v[90:93], v[164:167], v[230:233], v[90:93]
	v_mfma_f32_16x16x32_bf16 v[78:81], v[134:137], v[238:241], v[78:81]
	v_mfma_f32_16x16x32_bf16 v[74:77], v[164:167], v[238:241], v[74:77]
	s_setprio 0
	s_setprio 1
	v_mfma_f32_16x16x32_bf16 v[118:121], v[168:171], v[210:213], v[118:121]
	v_mfma_f32_16x16x32_bf16 v[114:117], v[202:205], v[210:213], v[114:117]
	v_mfma_f32_16x16x32_bf16 v[102:105], v[168:171], v[218:221], v[102:105]
	v_mfma_f32_16x16x32_bf16 v[98:101], v[202:205], v[218:221], v[98:101]
	v_mfma_f32_16x16x32_bf16 v[86:89], v[168:171], v[226:229], v[86:89]
	v_mfma_f32_16x16x32_bf16 v[82:85], v[202:205], v[226:229], v[82:85]
	v_mfma_f32_16x16x32_bf16 v[70:73], v[168:171], v[234:237], v[70:73]
	v_mfma_f32_16x16x32_bf16 v[66:69], v[202:205], v[234:237], v[66:69]
	v_mfma_f32_16x16x32_bf16 v[118:121], v[172:175], v[214:217], v[118:121]
	v_mfma_f32_16x16x32_bf16 v[114:117], v[206:209], v[214:217], v[114:117]
	v_mfma_f32_16x16x32_bf16 v[102:105], v[172:175], v[222:225], v[102:105]
	v_mfma_f32_16x16x32_bf16 v[98:101], v[206:209], v[222:225], v[98:101]
	v_mfma_f32_16x16x32_bf16 v[86:89], v[172:175], v[230:233], v[86:89]
	v_mfma_f32_16x16x32_bf16 v[82:85], v[206:209], v[230:233], v[82:85]
	v_mfma_f32_16x16x32_bf16 v[70:73], v[172:175], v[238:241], v[70:73]
	v_mfma_f32_16x16x32_bf16 v[66:69], v[206:209], v[238:241], v[66:69]
	s_setprio 0
	s_barrier
	s_add_i32 s41, s41, s79
	s_mov_b32 m0, s41
	ds_read_b128 v[210:213], v201 offset:16384
	ds_read_b128 v[214:217], v201 offset:17408
	ds_read_b128 v[218:221], v201 offset:18432
	ds_read_b128 v[222:225], v201 offset:19456
	ds_read_b128 v[226:229], v201 offset:20480
	ds_read_b128 v[230:233], v201 offset:21504
	ds_read_b128 v[234:237], v201 offset:22528
	ds_read_b128 v[238:241], v201 offset:23552
	global_load_lds_dwordx4 v146, s[44:45]
	s_add_i32 m0, s41, 0x2000
	s_add_u32 s98, s44, 0x80
	s_addc_u32 s99, s45, 0
	global_load_lds_dwordx4 v150, s[44:45]
	s_add_u32 s44, s44, s76
	s_addc_u32 s45, s45, 0
	s_add_i32 s23, s23, s79
	s_mov_b32 m0, s23
	s_add_u32 s100, s10, 0x80
	s_addc_u32 s101, s11, 0
	global_load_lds_dwordx4 v146, s[44:45]
	s_add_i32 m0, s23, 0x2000
	s_nop 0
	global_load_lds_dwordx4 v150, s[44:45]
	s_mov_b32 m0, s29
	s_nop 0
	global_load_lds_dwordx4 v144, s[10:11]
	s_mov_b32 m0, s93
	s_nop 0
	global_load_lds_dwordx4 v148, s[10:11]
	s_waitcnt vmcnt(8)
	s_waitcnt lgkmcnt(0)
	s_barrier
	s_setprio 1
	s_waitcnt lgkmcnt(0)
	v_mfma_f32_16x16x32_bf16 v[62:65], v[130:133], v[210:213], v[62:65]
	v_mfma_f32_16x16x32_bf16 v[58:61], v[160:163], v[210:213], v[58:61]
	v_mfma_f32_16x16x32_bf16 v[46:49], v[130:133], v[218:221], v[46:49]
	v_mfma_f32_16x16x32_bf16 v[42:45], v[160:163], v[218:221], v[42:45]
	v_mfma_f32_16x16x32_bf16 v[30:33], v[130:133], v[226:229], v[30:33]
	v_mfma_f32_16x16x32_bf16 v[26:29], v[160:163], v[226:229], v[26:29]
	v_mfma_f32_16x16x32_bf16 v[14:17], v[130:133], v[234:237], v[14:17]
	v_mfma_f32_16x16x32_bf16 v[10:13], v[160:163], v[234:237], v[10:13]
	v_mfma_f32_16x16x32_bf16 v[62:65], v[134:137], v[214:217], v[62:65]
	v_mfma_f32_16x16x32_bf16 v[58:61], v[164:167], v[214:217], v[58:61]
	v_mfma_f32_16x16x32_bf16 v[46:49], v[134:137], v[222:225], v[46:49]
	v_mfma_f32_16x16x32_bf16 v[42:45], v[164:167], v[222:225], v[42:45]
	v_mfma_f32_16x16x32_bf16 v[30:33], v[134:137], v[230:233], v[30:33]
	v_mfma_f32_16x16x32_bf16 v[26:29], v[164:167], v[230:233], v[26:29]
	v_mfma_f32_16x16x32_bf16 v[14:17], v[134:137], v[238:241], v[14:17]
	v_mfma_f32_16x16x32_bf16 v[10:13], v[164:167], v[238:241], v[10:13]
	s_setprio 0
	s_setprio 1
	v_mfma_f32_16x16x32_bf16 v[54:57], v[168:171], v[210:213], v[54:57]
	v_mfma_f32_16x16x32_bf16 v[50:53], v[202:205], v[210:213], v[50:53]
	v_mfma_f32_16x16x32_bf16 v[38:41], v[168:171], v[218:221], v[38:41]
	v_mfma_f32_16x16x32_bf16 v[34:37], v[202:205], v[218:221], v[34:37]
	v_mfma_f32_16x16x32_bf16 v[22:25], v[168:171], v[226:229], v[22:25]
	v_mfma_f32_16x16x32_bf16 v[18:21], v[202:205], v[226:229], v[18:21]
	v_mfma_f32_16x16x32_bf16 v[6:9], v[168:171], v[234:237], v[6:9]
	v_mfma_f32_16x16x32_bf16 v[2:5], v[202:205], v[234:237], v[2:5]
	v_mfma_f32_16x16x32_bf16 v[54:57], v[172:175], v[214:217], v[54:57]
	v_mfma_f32_16x16x32_bf16 v[50:53], v[206:209], v[214:217], v[50:53]
	v_mfma_f32_16x16x32_bf16 v[38:41], v[172:175], v[222:225], v[38:41]
	v_mfma_f32_16x16x32_bf16 v[34:37], v[206:209], v[222:225], v[34:37]
	v_mfma_f32_16x16x32_bf16 v[22:25], v[172:175], v[230:233], v[22:25]
	v_mfma_f32_16x16x32_bf16 v[18:21], v[206:209], v[230:233], v[18:21]
	v_mfma_f32_16x16x32_bf16 v[6:9], v[172:175], v[238:241], v[6:9]
	v_mfma_f32_16x16x32_bf16 v[2:5], v[206:209], v[238:241], v[2:5]
	s_setprio 0
	s_barrier
	s_add_i32 s23, 0, 0x18000
	v_add_u32_e32 v0, s23, v153
	s_add_i32 s41, 0, 0x1c000
	ds_read_b128 v[130:133], v0
	ds_read_b128 v[134:137], v0 offset:1024
	ds_read_b128 v[160:163], v0 offset:2048
	ds_read_b128 v[164:167], v0 offset:3072
	v_add_u32_e32 v0, s41, v153
	ds_read_b128 v[168:171], v0
	ds_read_b128 v[172:175], v0 offset:1024
	ds_read_b128 v[202:205], v0 offset:2048
	ds_read_b128 v[206:209], v0 offset:3072
	s_add_u32 s10, s10, s76
	s_addc_u32 s11, s11, 0
	s_mov_b32 m0, s52
	ds_read_b128 v[210:213], v201 offset:32768
	ds_read_b128 v[214:217], v201 offset:33792
	ds_read_b128 v[218:221], v201 offset:34816
	ds_read_b128 v[222:225], v201 offset:35840
	ds_read_b128 v[226:229], v201 offset:36864
	ds_read_b128 v[230:233], v201 offset:37888
	ds_read_b128 v[234:237], v201 offset:38912
	ds_read_b128 v[238:241], v201 offset:39936
	global_load_lds_dwordx4 v144, s[10:11]
	s_mov_b32 m0, s53
	s_nop 0
	global_load_lds_dwordx4 v148, s[10:11]
	s_waitcnt vmcnt(8)
	s_waitcnt lgkmcnt(0)
	s_barrier
	s_setprio 1
	s_waitcnt lgkmcnt(0)
	v_mfma_f32_16x16x32_bf16 v[126:129], v[130:133], v[210:213], v[126:129]
	v_mfma_f32_16x16x32_bf16 v[122:125], v[160:163], v[210:213], v[122:125]
	v_mfma_f32_16x16x32_bf16 v[110:113], v[130:133], v[218:221], v[110:113]
	v_mfma_f32_16x16x32_bf16 v[106:109], v[160:163], v[218:221], v[106:109]
	v_mfma_f32_16x16x32_bf16 v[94:97], v[130:133], v[226:229], v[94:97]
	v_mfma_f32_16x16x32_bf16 v[90:93], v[160:163], v[226:229], v[90:93]
	v_mfma_f32_16x16x32_bf16 v[78:81], v[130:133], v[234:237], v[78:81]
	v_mfma_f32_16x16x32_bf16 v[74:77], v[160:163], v[234:237], v[74:77]
	v_mfma_f32_16x16x32_bf16 v[126:129], v[134:137], v[214:217], v[126:129]
	v_mfma_f32_16x16x32_bf16 v[122:125], v[164:167], v[214:217], v[122:125]
	v_mfma_f32_16x16x32_bf16 v[110:113], v[134:137], v[222:225], v[110:113]
	v_mfma_f32_16x16x32_bf16 v[106:109], v[164:167], v[222:225], v[106:109]
	v_mfma_f32_16x16x32_bf16 v[94:97], v[134:137], v[230:233], v[94:97]
	v_mfma_f32_16x16x32_bf16 v[90:93], v[164:167], v[230:233], v[90:93]
	v_mfma_f32_16x16x32_bf16 v[78:81], v[134:137], v[238:241], v[78:81]
	v_mfma_f32_16x16x32_bf16 v[74:77], v[164:167], v[238:241], v[74:77]
	s_setprio 0
	s_setprio 1
	v_mfma_f32_16x16x32_bf16 v[118:121], v[168:171], v[210:213], v[118:121]
	v_mfma_f32_16x16x32_bf16 v[114:117], v[202:205], v[210:213], v[114:117]
	v_mfma_f32_16x16x32_bf16 v[102:105], v[168:171], v[218:221], v[102:105]
	v_mfma_f32_16x16x32_bf16 v[98:101], v[202:205], v[218:221], v[98:101]
	v_mfma_f32_16x16x32_bf16 v[86:89], v[168:171], v[226:229], v[86:89]
	v_mfma_f32_16x16x32_bf16 v[82:85], v[202:205], v[226:229], v[82:85]
	v_mfma_f32_16x16x32_bf16 v[70:73], v[168:171], v[234:237], v[70:73]
	v_mfma_f32_16x16x32_bf16 v[66:69], v[202:205], v[234:237], v[66:69]
	v_mfma_f32_16x16x32_bf16 v[118:121], v[172:175], v[214:217], v[118:121]
	v_mfma_f32_16x16x32_bf16 v[114:117], v[206:209], v[214:217], v[114:117]
	v_mfma_f32_16x16x32_bf16 v[102:105], v[172:175], v[222:225], v[102:105]
	v_mfma_f32_16x16x32_bf16 v[98:101], v[206:209], v[222:225], v[98:101]
	v_mfma_f32_16x16x32_bf16 v[86:89], v[172:175], v[230:233], v[86:89]
	v_mfma_f32_16x16x32_bf16 v[82:85], v[206:209], v[230:233], v[82:85]
	v_mfma_f32_16x16x32_bf16 v[70:73], v[172:175], v[238:241], v[70:73]
	v_mfma_f32_16x16x32_bf16 v[66:69], v[206:209], v[238:241], v[66:69]
	s_setprio 0
	s_barrier
	s_add_i32 s10, s23, s79
	s_mov_b32 m0, s10
	ds_read_b128 v[210:213], v201 offset:49152
	ds_read_b128 v[214:217], v201 offset:50176
	ds_read_b128 v[218:221], v201 offset:51200
	ds_read_b128 v[222:225], v201 offset:52224
	ds_read_b128 v[226:229], v201 offset:53248
	ds_read_b128 v[230:233], v201 offset:54272
	ds_read_b128 v[234:237], v201 offset:55296
	ds_read_b128 v[238:241], v201 offset:56320
	global_load_lds_dwordx4 v146, s[98:99]
	s_add_i32 m0, s10, 0x2000
	s_add_i32 s10, s41, s79
	global_load_lds_dwordx4 v150, s[98:99]
	s_add_u32 s98, s98, s76
	s_addc_u32 s99, s99, 0
	s_mov_b32 m0, s10
	s_nop 0
	global_load_lds_dwordx4 v146, s[98:99]
	s_add_i32 m0, s10, 0x2000
	s_nop 0
	global_load_lds_dwordx4 v150, s[98:99]
	s_mov_b32 m0, s26
	s_nop 0
	global_load_lds_dwordx4 v144, s[100:101]
	s_mov_b32 m0, s27
	s_nop 0
	global_load_lds_dwordx4 v148, s[100:101]
	s_waitcnt vmcnt(8)
	s_waitcnt lgkmcnt(0)
	s_barrier
	s_setprio 1
	s_waitcnt lgkmcnt(0)
	v_mfma_f32_16x16x32_bf16 v[62:65], v[130:133], v[210:213], v[62:65]
	v_mfma_f32_16x16x32_bf16 v[58:61], v[160:163], v[210:213], v[58:61]
	v_mfma_f32_16x16x32_bf16 v[46:49], v[130:133], v[218:221], v[46:49]
	v_mfma_f32_16x16x32_bf16 v[42:45], v[160:163], v[218:221], v[42:45]
	v_mfma_f32_16x16x32_bf16 v[30:33], v[130:133], v[226:229], v[30:33]
	v_mfma_f32_16x16x32_bf16 v[26:29], v[160:163], v[226:229], v[26:29]
	v_mfma_f32_16x16x32_bf16 v[14:17], v[130:133], v[234:237], v[14:17]
	v_mfma_f32_16x16x32_bf16 v[10:13], v[160:163], v[234:237], v[10:13]
	v_mfma_f32_16x16x32_bf16 v[62:65], v[134:137], v[214:217], v[62:65]
	v_mfma_f32_16x16x32_bf16 v[58:61], v[164:167], v[214:217], v[58:61]
	v_mfma_f32_16x16x32_bf16 v[46:49], v[134:137], v[222:225], v[46:49]
	v_mfma_f32_16x16x32_bf16 v[42:45], v[164:167], v[222:225], v[42:45]
	v_mfma_f32_16x16x32_bf16 v[30:33], v[134:137], v[230:233], v[30:33]
	v_mfma_f32_16x16x32_bf16 v[26:29], v[164:167], v[230:233], v[26:29]
	v_mfma_f32_16x16x32_bf16 v[14:17], v[134:137], v[238:241], v[14:17]
	v_mfma_f32_16x16x32_bf16 v[10:13], v[164:167], v[238:241], v[10:13]
	s_setprio 0
	s_setprio 1
	v_mfma_f32_16x16x32_bf16 v[54:57], v[168:171], v[210:213], v[54:57]
	v_mfma_f32_16x16x32_bf16 v[50:53], v[202:205], v[210:213], v[50:53]
	v_mfma_f32_16x16x32_bf16 v[38:41], v[168:171], v[218:221], v[38:41]
	v_mfma_f32_16x16x32_bf16 v[34:37], v[202:205], v[218:221], v[34:37]
	v_mfma_f32_16x16x32_bf16 v[22:25], v[168:171], v[226:229], v[22:25]
	v_mfma_f32_16x16x32_bf16 v[18:21], v[202:205], v[226:229], v[18:21]
	v_mfma_f32_16x16x32_bf16 v[6:9], v[168:171], v[234:237], v[6:9]
	v_mfma_f32_16x16x32_bf16 v[2:5], v[202:205], v[234:237], v[2:5]
	v_mfma_f32_16x16x32_bf16 v[54:57], v[172:175], v[214:217], v[54:57]
	v_mfma_f32_16x16x32_bf16 v[50:53], v[206:209], v[214:217], v[50:53]
	v_mfma_f32_16x16x32_bf16 v[38:41], v[172:175], v[222:225], v[38:41]
	v_mfma_f32_16x16x32_bf16 v[34:37], v[206:209], v[222:225], v[34:37]
	v_mfma_f32_16x16x32_bf16 v[22:25], v[172:175], v[230:233], v[22:25]
	v_mfma_f32_16x16x32_bf16 v[18:21], v[206:209], v[230:233], v[18:21]
	v_mfma_f32_16x16x32_bf16 v[6:9], v[172:175], v[238:241], v[6:9]
	v_mfma_f32_16x16x32_bf16 v[2:5], v[206:209], v[238:241], v[2:5]
	s_setprio 0
	s_barrier
	s_add_u32 s2, s2, 0x100
	s_addc_u32 s3, s3, 0
	s_add_u32 s20, s20, 0x100
	s_addc_u32 s21, s21, 0
	s_cmp_ge_u32 s22, s63
	s_mov_b32 s10, s22
	s_cbranch_scc0 .LBB0_294
	v_readlane_b32 s2, v255, 24
	v_readlane_b32 s3, v255, 25
	s_and_b64 vcc, exec, s[2:3]
	s_cbranch_vccz .LBB0_297
	s_barrier

	.amdhsa_kernel _Z10fwd_kernel4Args
		.amdhsa_group_segment_fixed_size 0
		.amdhsa_private_segment_fixed_size 0
		.amdhsa_kernarg_size 456
		.amdhsa_user_sgpr_count 2
		.amdhsa_user_sgpr_dispatch_ptr 0
		.amdhsa_user_sgpr_queue_ptr 0
		.amdhsa_user_sgpr_kernarg_segment_ptr 1
		.amdhsa_user_sgpr_dispatch_id 0
		.amdhsa_user_sgpr_kernarg_preload_length 0
		.amdhsa_user_sgpr_kernarg_preload_offset 0
		.amdhsa_user_sgpr_private_segment_size 0
		.amdhsa_uses_dynamic_stack 0
		.amdhsa_enable_private_segment 0
		.amdhsa_system_sgpr_workgroup_id_x 1
		.amdhsa_system_sgpr_workgroup_id_y 0
		.amdhsa_system_sgpr_workgroup_id_z 0
		.amdhsa_system_sgpr_workgroup_info 0
		.amdhsa_system_vgpr_workitem_id 2
		.amdhsa_next_free_vgpr 256
		.amdhsa_next_free_sgpr 102
		.amdhsa_accum_offset 256
		.amdhsa_reserve_vcc 1
		.amdhsa_float_round_mode_32 0
		.amdhsa_float_round_mode_16_64 0
		.amdhsa_float_denorm_mode_32 3
		.amdhsa_float_denorm_mode_16_64 3
		.amdhsa_dx10_clamp 1
		.amdhsa_ieee_mode 1
		.amdhsa_fp16_overflow 0
		.amdhsa_tg_split 0
		.amdhsa_exception_fp_ieee_invalid_op 0
		.amdhsa_exception_fp_denorm_src 0
		.amdhsa_exception_fp_ieee_div_zero 0
		.amdhsa_exception_fp_ieee_overflow 0
		.amdhsa_exception_fp_ieee_underflow 0
		.amdhsa_exception_fp_ieee_inexact 0
		.amdhsa_exception_int_div_zero 0
	.end_amdhsa_kernel

amdhsa.kernels:
  - .agpr_count:     0
    .args:
      - .offset:         0
        .size:           200
        .value_kind:     by_value
      - .offset:         200
        .size:           4
        .value_kind:     hidden_block_count_x
      - .offset:         204
        .size:           4
        .value_kind:     hidden_block_count_y
      - .offset:         208
        .size:           4
        .value_kind:     hidden_block_count_z
      - .offset:         212
        .size:           2
        .value_kind:     hidden_group_size_x
      - .offset:         214
        .size:           2
        .value_kind:     hidden_group_size_y
      - .offset:         216
        .size:           2
        .value_kind:     hidden_group_size_z
      - .offset:         218
        .size:           2
        .value_kind:     hidden_remainder_x
      - .offset:         220
        .size:           2
        .value_kind:     hidden_remainder_y
      - .offset:         222
        .size:           2
        .value_kind:     hidden_remainder_z
      - .offset:         240
        .size:           8
        .value_kind:     hidden_global_offset_x
      - .offset:         248
        .size:           8
        .value_kind:     hidden_global_offset_y
      - .offset:         256
        .size:           8
        .value_kind:     hidden_global_offset_z
      - .offset:         264
        .size:           2
        .value_kind:     hidden_grid_dims
      - .offset:         288
        .size:           8
        .value_kind:     hidden_multigrid_sync_arg
      - .offset:         320
        .size:           4
        .value_kind:     hidden_dynamic_lds_size
    .group_segment_fixed_size: 0
    .kernarg_segment_align: 8
    .kernarg_segment_size: 456
    .language:       OpenCL C
    .language_version:
      - 2
      - 0
    .max_flat_workgroup_size: 512
    .name:           _Z10fwd_kernel4Args
    .private_segment_fixed_size: 0
    .sgpr_count:     108
    .sgpr_spill_count: 234
    .symbol:         _Z10fwd_kernel4Args.kd
    .uniform_work_group_size: 1
    .uses_dynamic_stack: false
    .vgpr_count:     256
    .vgpr_spill_count: 0
    .wavefront_size: 64
